# FFN-up silu epilogue: scalar mul/add pairs packed (v_pk_mul_f32 with SGPR constant, v_pk_add_f32 1.0), on top of v112
# speedup vs baseline: 1.0070x; 1.0026x over previous
.LBB0_1526:
	s_or_b64 exec, exec, s[4:5]
	s_mul_i32 s1, s26, 0xb00000
	s_mul_hi_u32 s0, s26, 0xb00000
	s_add_u32 s8, s1, 0x1200000
	s_mov_b64 s[2:3], 0x6500800
	s_addc_u32 s9, s0, 0
	s_mov_b64 s[6:7], 0x8800000
	s_waitcnt lgkmcnt(0)
	s_barrier
	s_mov_b32 s100, 0xbfb8aa3b
	s_mov_b32 s101, 0xbfb8aa3b
	s_getreg_b32 s0, hwreg(HW_REG_HW_ID, 0, 6)
	s_and_b32 s0, s0, 63
	s_lshl_b32 s0, s0, 2
	s_add_i32 s0, s0, 0
	s_add_i32 s0, s0, 0x22ef0
	v_mov_b32_e32 v0, s0
	ds_read_b32 v0, v0
	s_movk_i32 s4, 0x400
	s_waitcnt lgkmcnt(0)
	v_readfirstlane_b32 s0, v0
	v_mov_b32_e32 v0, v177
	s_nop 0
	v_mbcnt_lo_u32_b32 v0, -1, v0
	v_mbcnt_hi_u32_b32 v0, -1, v0
	v_lshl_add_u32 v12, s0, 6, v0
	v_readlane_b32 s0, v253, 31
	v_readlane_b32 s1, v253, 32
	s_andn2_b64 vcc, exec, s[0:1]
	v_readfirstlane_b32 s16, v12
	s_cbranch_vccnz .LBB0_1545
	v_lshlrev_b32_e32 v0, 4, v12
	v_add_u32_e32 v1, 0x2000, v0
	v_ashrrev_i32_e32 v2, 31, v1
	v_lshrrev_b32_e32 v2, 22, v2
	v_add_u32_e32 v2, v1, v2
	v_ashrrev_i32_e32 v13, 10, v2
	v_mul_i32_i24_e32 v3, 0x400, v13
	v_sub_u32_e32 v1, v1, v3
	v_lshrrev_b32_e32 v3, 4, v1
	v_bitop3_b32 v1, v3, v1, 32 bitop3:0x6c
	v_ashrrev_i32_e32 v3, 31, v1
	v_lshrrev_b32_e32 v3, 26, v3
	v_add_u32_e32 v3, v1, v3
	v_ashrrev_i32_e32 v14, 6, v3
	v_and_b32_e32 v3, 0xc0, v3
	v_sub_u32_e32 v1, v1, v3
	v_mov_b32_e32 v4, 1
	v_lshlrev_b32_e32 v2, 5, v13
	v_ashrrev_i16_sdwa v1, v4, sext(v1) dst_sel:DWORD dst_unused:UNUSED_PAD src0_sel:DWORD src1_sel:BYTE_0
	v_and_b32_e32 v2, 32, v2
	v_bfe_i32 v15, v1, 0, 16
	v_add_u32_e32 v1, v2, v15
	v_lshlrev_b32_e32 v2, 3, v13
	v_and_b32_e32 v2, -16, v2
	v_add_u32_e32 v2, v14, v2
	v_mul_lo_u32 v3, v2, s4
	v_lshlrev_b32_e32 v2, 11, v2
	v_lshl_add_u32 v130, v1, 1, v2
	v_bfe_i32 v2, v12, 27, 1
	v_lshrrev_b32_e32 v2, 22, v2
	v_add_u32_e32 v2, v0, v2
	v_and_b32_e32 v2, 0xfffffc00, v2
	v_sub_u32_e32 v0, v0, v2
	v_lshrrev_b32_e32 v2, 4, v0
	v_bitop3_b32 v2, v2, v0, 32 bitop3:0x6c
	v_ashrrev_i32_e32 v0, 31, v0
	v_lshrrev_b32_e32 v0, 26, v0
	s_add_u32 s26, s66, s2
	v_add_lshl_u32 v128, v1, v3, 1
	v_ashrrev_i32_e32 v1, 31, v12
	v_add_u32_e32 v0, v2, v0
	s_addc_u32 s27, s67, s3
	v_lshrrev_b32_e32 v1, 26, v1
	v_ashrrev_i32_e32 v17, 6, v0
	s_add_u32 s28, s66, s8
	v_add_u32_e32 v1, v12, v1
	v_mul_i32_i24_e32 v0, 64, v17
	s_addc_u32 s29, s67, s9
	s_ashr_i32 s5, s4, 31
	v_ashrrev_i32_e32 v16, 6, v1
	v_sub_u32_e32 v0, v2, v0
	v_readlane_b32 s12, v253, 55
	s_lshl_b64 s[10:11], s[4:5], 9
	v_lshlrev_b32_e32 v1, 5, v16
	v_ashrrev_i16_sdwa v0, v4, sext(v0) dst_sel:DWORD dst_unused:UNUSED_PAD src0_sel:DWORD src1_sel:BYTE_0
	v_readlane_b32 s13, v253, 56
	v_and_b32_e32 v1, 32, v1
	v_bfe_i32 v18, v0, 0, 16
	s_mul_i32 s0, s10, s13
	s_mul_hi_u32 s1, s10, s12
	s_lshr_b64 s[2:3], s[4:5], 23
	s_ashr_i32 s15, s16, 6
	v_add_u32_e32 v0, v1, v18
	v_lshlrev_b32_e32 v1, 3, v16
	s_add_i32 s0, s1, s0
	s_mul_i32 s1, s2, s12
	s_ashr_i32 s14, s16, 8
	s_lshl_b64 s[8:9], s[4:5], 8
	s_lshl_b32 s30, s15, 10
	v_and_b32_e32 v1, -16, v1
	s_add_i32 s0, s0, s1
	s_mul_i32 s1, s10, s12
	v_add_u32_e32 v1, v17, v1
	s_add_u32 s24, s28, s1
	v_mul_lo_u32 v2, v1, s4
	s_addc_u32 s25, s29, s0
	s_add_i32 s31, s30, 0
	v_add_lshl_u32 v176, v0, v2, 1
	s_add_i32 m0, s31, 0x10000
	v_readlane_b32 s0, v254, 5
	global_load_lds_dwordx4 v176, s[24:25]
	s_add_i32 m0, s31, 0x12000
	v_readlane_b32 s1, v254, 6
	s_add_u32 s0, s26, s0
	s_addc_u32 s1, s27, s1
	s_add_u32 s2, s24, s8
	global_load_lds_dwordx4 v128, s[24:25]
	s_addc_u32 s3, s25, s9
	s_add_i32 m0, s31, 0x14000
	v_mov_b32_e32 v129, v177
	global_load_lds_dwordx4 v176, s[2:3]
	s_add_i32 m0, s31, 0x16000
	v_lshl_add_u64 v[4:5], s[2:3], 0, v[176:177]
	v_lshl_add_u64 v[6:7], s[2:3], 0, v[128:129]
	global_load_lds_dwordx4 v128, s[2:3]
	v_readlane_b32 s2, v253, 53
	v_readlane_b32 s3, v253, 54
	s_add_u32 s2, s0, s2
	v_lshlrev_b32_e32 v1, 11, v1
	s_addc_u32 s3, s1, s3
	s_add_i32 s33, s31, 0x2000
	v_lshl_add_u32 v132, v0, 1, v1
	s_mov_b32 m0, s31
	s_add_u32 s12, s2, 0x40000
	global_load_lds_dwordx4 v132, s[2:3]
	s_mov_b32 m0, s33
	s_addc_u32 s13, s3, 0
	s_add_i32 s34, s31, 0x4000
	global_load_lds_dwordx4 v130, s[2:3]
	s_mov_b32 m0, s34
	s_add_i32 s35, s31, 0x6000
	global_load_lds_dwordx4 v132, s[12:13]
	s_mov_b32 m0, s35
	v_mov_b32_e32 v133, v177
	global_load_lds_dwordx4 v130, s[12:13]
	v_mov_b32_e32 v131, v177
	s_cmp_eq_u32 s14, 1
	v_lshl_add_u64 v[0:1], s[24:25], 0, v[176:177]
	v_lshl_add_u64 v[2:3], s[24:25], 0, v[128:129]
	v_lshl_add_u64 v[8:9], s[2:3], 0, v[132:133]
	v_lshl_add_u64 v[10:11], s[2:3], 0, v[130:131]
	s_cselect_b64 s[12:13], -1, 0
	s_cmp_lg_u32 s14, 1
	s_cbranch_scc1 .LBB0_1529
	s_barrier

.LBB0_1541:
	v_pk_mul_f32 v[146:147], v[120:121], s[100:101]
	v_exp_f32_e32 v146, v146
	v_exp_f32_e32 v147, v147
	s_lshl_b32 s0, s46, 7
	v_lshl_add_u32 v143, s47, 8, v140
	v_pk_add_f32 v[146:147], v[146:147], 1.0 op_sel_hi:[1,0]
	v_rcp_f32_e32 v146, v146
	v_rcp_f32_e32 v147, v147
	s_or_b32 s2, s0, s42
	s_movk_i32 s0, 0x1600
	v_mad_i64_i32 v[144:145], s[6:7], v143, s0, v[134:135]
	v_pk_mul_f32 v[120:121], v[120:121], v[146:147]
	s_ashr_i32 s3, s2, 31
	v_pk_mul_f32 v[120:121], v[124:125], v[120:121]
	v_pk_mul_f32 v[124:125], v[122:123], s[100:101]
	v_exp_f32_e32 v124, v124
	v_exp_f32_e32 v125, v125
	s_lshl_b64 s[6:7], s[2:3], 1
	v_cvt_pk_bf16_f32 v120, v120, v121
	v_pk_add_f32 v[124:125], v[124:125], 1.0 op_sel_hi:[1,0]
	v_rcp_f32_e32 v124, v124
	v_rcp_f32_e32 v125, v125
	s_and_b64 vcc, exec, s[4:5]
	v_pk_mul_f32 v[122:123], v[122:123], v[124:125]
	s_nop 0
	v_pk_mul_f32 v[122:123], v[126:127], v[122:123]
	v_lshl_add_u64 v[124:125], v[144:145], 0, s[6:7]
	v_cvt_pk_bf16_f32 v121, v122, v123
	global_store_dwordx2 v[124:125], v[120:121], off
	v_pk_mul_f32 v[120:121], v[116:117], s[100:101]
	v_exp_f32_e32 v120, v120
	v_exp_f32_e32 v121, v121
	s_nop 0
	v_pk_add_f32 v[120:121], v[120:121], 1.0 op_sel_hi:[1,0]
	v_rcp_f32_e32 v120, v120
	v_rcp_f32_e32 v121, v121
	s_nop 0
	v_pk_mul_f32 v[116:117], v[116:117], v[120:121]
	s_nop 0
	v_pk_mul_f32 v[112:113], v[112:113], v[116:117]
	v_pk_mul_f32 v[116:117], v[118:119], s[100:101]
	v_exp_f32_e32 v116, v116
	v_exp_f32_e32 v117, v117
	v_cvt_pk_bf16_f32 v112, v112, v113
	v_pk_add_f32 v[116:117], v[116:117], 1.0 op_sel_hi:[1,0]
	v_rcp_f32_e32 v116, v116
	v_rcp_f32_e32 v117, v117
	s_nop 0
	v_pk_mul_f32 v[116:117], v[118:119], v[116:117]
	s_nop 0
	v_pk_mul_f32 v[114:115], v[114:115], v[116:117]
	s_nop 0
	v_cvt_pk_bf16_f32 v113, v114, v115
	v_pk_mul_f32 v[114:115], v[108:109], s[100:101]
	v_exp_f32_e32 v114, v114
	v_exp_f32_e32 v115, v115
	global_store_dwordx2 v[124:125], v[112:113], off offset:32
	v_or_b32_e32 v112, 16, v143
	v_pk_add_f32 v[114:115], v[114:115], 1.0 op_sel_hi:[1,0]
	v_rcp_f32_e32 v114, v114
	v_rcp_f32_e32 v115, v115
	v_mad_i64_i32 v[112:113], s[2:3], v112, s0, v[134:135]
	v_pk_mul_f32 v[108:109], v[108:109], v[114:115]
	s_nop 0
	v_pk_mul_f32 v[104:105], v[104:105], v[108:109]
	v_pk_mul_f32 v[108:109], v[110:111], s[100:101]
	v_exp_f32_e32 v108, v108
	v_exp_f32_e32 v109, v109
	v_cvt_pk_bf16_f32 v104, v104, v105
	v_pk_add_f32 v[108:109], v[108:109], 1.0 op_sel_hi:[1,0]
	v_rcp_f32_e32 v108, v108
	v_rcp_f32_e32 v109, v109
	s_nop 0
	v_pk_mul_f32 v[108:109], v[110:111], v[108:109]
	s_nop 0
	v_pk_mul_f32 v[106:107], v[106:107], v[108:109]
	v_lshl_add_u64 v[108:109], v[112:113], 0, s[6:7]
	v_cvt_pk_bf16_f32 v105, v106, v107
	global_store_dwordx2 v[108:109], v[104:105], off
	v_pk_mul_f32 v[104:105], v[100:101], s[100:101]
	v_exp_f32_e32 v104, v104
	v_exp_f32_e32 v105, v105
	s_nop 0
	v_pk_add_f32 v[104:105], v[104:105], 1.0 op_sel_hi:[1,0]
	v_rcp_f32_e32 v104, v104
	v_rcp_f32_e32 v105, v105
	s_nop 0
	v_pk_mul_f32 v[100:101], v[100:101], v[104:105]
	s_nop 0
	v_pk_mul_f32 v[96:97], v[96:97], v[100:101]
	v_pk_mul_f32 v[100:101], v[102:103], s[100:101]
	v_exp_f32_e32 v100, v100
	v_exp_f32_e32 v101, v101
	v_cvt_pk_bf16_f32 v96, v96, v97
	v_pk_add_f32 v[100:101], v[100:101], 1.0 op_sel_hi:[1,0]
	v_rcp_f32_e32 v100, v100
	v_rcp_f32_e32 v101, v101
	s_nop 0
	v_pk_mul_f32 v[100:101], v[102:103], v[100:101]
	s_nop 0
	v_pk_mul_f32 v[98:99], v[98:99], v[100:101]
	s_nop 0
	v_cvt_pk_bf16_f32 v97, v98, v99
	v_pk_mul_f32 v[98:99], v[92:93], s[100:101]
	v_exp_f32_e32 v98, v98
	v_exp_f32_e32 v99, v99
	global_store_dwordx2 v[108:109], v[96:97], off offset:32
	v_or_b32_e32 v96, 32, v143
	v_pk_add_f32 v[98:99], v[98:99], 1.0 op_sel_hi:[1,0]
	v_rcp_f32_e32 v98, v98
	v_rcp_f32_e32 v99, v99
	v_mad_i64_i32 v[96:97], s[2:3], v96, s0, v[134:135]
	v_pk_mul_f32 v[92:93], v[92:93], v[98:99]
	s_nop 0
	v_pk_mul_f32 v[88:89], v[88:89], v[92:93]
	v_pk_mul_f32 v[92:93], v[94:95], s[100:101]
	v_exp_f32_e32 v92, v92
	v_exp_f32_e32 v93, v93
	v_cvt_pk_bf16_f32 v88, v88, v89
	v_pk_add_f32 v[92:93], v[92:93], 1.0 op_sel_hi:[1,0]
	v_rcp_f32_e32 v92, v92
	v_rcp_f32_e32 v93, v93
	s_nop 0
	v_pk_mul_f32 v[92:93], v[94:95], v[92:93]
	s_nop 0
	v_pk_mul_f32 v[90:91], v[90:91], v[92:93]
	v_lshl_add_u64 v[92:93], v[96:97], 0, s[6:7]
	v_cvt_pk_bf16_f32 v89, v90, v91
	global_store_dwordx2 v[92:93], v[88:89], off
	v_pk_mul_f32 v[88:89], v[84:85], s[100:101]
	v_exp_f32_e32 v88, v88
	v_exp_f32_e32 v89, v89
	s_nop 0
	v_pk_add_f32 v[88:89], v[88:89], 1.0 op_sel_hi:[1,0]
	v_rcp_f32_e32 v88, v88
	v_rcp_f32_e32 v89, v89
	s_nop 0
	v_pk_mul_f32 v[84:85], v[84:85], v[88:89]
	s_nop 0
	v_pk_mul_f32 v[80:81], v[80:81], v[84:85]
	v_pk_mul_f32 v[84:85], v[86:87], s[100:101]
	v_exp_f32_e32 v84, v84
	v_exp_f32_e32 v85, v85
	v_cvt_pk_bf16_f32 v80, v80, v81
	v_pk_add_f32 v[84:85], v[84:85], 1.0 op_sel_hi:[1,0]
	v_rcp_f32_e32 v84, v84
	v_rcp_f32_e32 v85, v85
	s_nop 0
	v_pk_mul_f32 v[84:85], v[86:87], v[84:85]
	s_nop 0
	v_pk_mul_f32 v[82:83], v[82:83], v[84:85]
	s_nop 0
	v_cvt_pk_bf16_f32 v81, v82, v83
	v_pk_mul_f32 v[82:83], v[76:77], s[100:101]
	v_exp_f32_e32 v82, v82
	v_exp_f32_e32 v83, v83
	global_store_dwordx2 v[92:93], v[80:81], off offset:32
	v_or_b32_e32 v80, 48, v143
	v_pk_add_f32 v[82:83], v[82:83], 1.0 op_sel_hi:[1,0]
	v_rcp_f32_e32 v82, v82
	v_rcp_f32_e32 v83, v83
	v_mad_i64_i32 v[80:81], s[2:3], v80, s0, v[134:135]
	v_pk_mul_f32 v[76:77], v[76:77], v[82:83]
	s_nop 0
	v_pk_mul_f32 v[72:73], v[72:73], v[76:77]
	v_pk_mul_f32 v[76:77], v[78:79], s[100:101]
	v_exp_f32_e32 v76, v76
	v_exp_f32_e32 v77, v77
	v_cvt_pk_bf16_f32 v72, v72, v73
	v_pk_add_f32 v[76:77], v[76:77], 1.0 op_sel_hi:[1,0]
	v_rcp_f32_e32 v76, v76
	v_rcp_f32_e32 v77, v77
	s_nop 0
	v_pk_mul_f32 v[76:77], v[78:79], v[76:77]
	s_nop 0
	v_pk_mul_f32 v[74:75], v[74:75], v[76:77]
	v_lshl_add_u64 v[76:77], v[80:81], 0, s[6:7]
	v_cvt_pk_bf16_f32 v73, v74, v75
	global_store_dwordx2 v[76:77], v[72:73], off
	v_pk_mul_f32 v[72:73], v[68:69], s[100:101]
	v_exp_f32_e32 v72, v72
	v_exp_f32_e32 v73, v73
	s_nop 0
	v_pk_add_f32 v[72:73], v[72:73], 1.0 op_sel_hi:[1,0]
	v_rcp_f32_e32 v72, v72
	v_rcp_f32_e32 v73, v73
	s_nop 0
	v_pk_mul_f32 v[68:69], v[68:69], v[72:73]
	s_nop 0
	v_pk_mul_f32 v[64:65], v[64:65], v[68:69]
	v_pk_mul_f32 v[68:69], v[70:71], s[100:101]
	v_exp_f32_e32 v68, v68
	v_exp_f32_e32 v69, v69
	v_cvt_pk_bf16_f32 v64, v64, v65
	v_pk_add_f32 v[68:69], v[68:69], 1.0 op_sel_hi:[1,0]
	v_rcp_f32_e32 v68, v68
	v_rcp_f32_e32 v69, v69
	s_nop 0
	v_pk_mul_f32 v[68:69], v[70:71], v[68:69]
	s_nop 0
	v_pk_mul_f32 v[66:67], v[66:67], v[68:69]
	s_nop 0
	v_cvt_pk_bf16_f32 v65, v66, v67
	v_pk_mul_f32 v[66:67], v[60:61], s[100:101]
	v_exp_f32_e32 v66, v66
	v_exp_f32_e32 v67, v67
	global_store_dwordx2 v[76:77], v[64:65], off offset:32
	v_add_u32_e32 v64, 0x80, v143
	v_pk_add_f32 v[66:67], v[66:67], 1.0 op_sel_hi:[1,0]
	v_rcp_f32_e32 v66, v66
	v_rcp_f32_e32 v67, v67
	v_mad_i64_i32 v[64:65], s[2:3], v64, s0, v[134:135]
	v_pk_mul_f32 v[60:61], v[60:61], v[66:67]
	s_nop 0
	v_pk_mul_f32 v[56:57], v[56:57], v[60:61]
	v_pk_mul_f32 v[60:61], v[62:63], s[100:101]
	v_exp_f32_e32 v60, v60
	v_exp_f32_e32 v61, v61
	v_cvt_pk_bf16_f32 v56, v56, v57
	v_pk_add_f32 v[60:61], v[60:61], 1.0 op_sel_hi:[1,0]
	v_rcp_f32_e32 v60, v60
	v_rcp_f32_e32 v61, v61
	s_nop 0
	v_pk_mul_f32 v[60:61], v[62:63], v[60:61]
	s_nop 0
	v_pk_mul_f32 v[58:59], v[58:59], v[60:61]
	v_lshl_add_u64 v[60:61], v[64:65], 0, s[6:7]
	v_cvt_pk_bf16_f32 v57, v58, v59
	global_store_dwordx2 v[60:61], v[56:57], off
	v_pk_mul_f32 v[56:57], v[52:53], s[100:101]
	v_exp_f32_e32 v56, v56
	v_exp_f32_e32 v57, v57
	s_nop 0
	v_pk_add_f32 v[56:57], v[56:57], 1.0 op_sel_hi:[1,0]
	v_rcp_f32_e32 v56, v56
	v_rcp_f32_e32 v57, v57
	s_nop 0
	v_pk_mul_f32 v[52:53], v[52:53], v[56:57]
	s_nop 0
	v_pk_mul_f32 v[48:49], v[48:49], v[52:53]
	v_pk_mul_f32 v[52:53], v[54:55], s[100:101]
	v_exp_f32_e32 v52, v52
	v_exp_f32_e32 v53, v53
	v_cvt_pk_bf16_f32 v48, v48, v49
	v_pk_add_f32 v[52:53], v[52:53], 1.0 op_sel_hi:[1,0]
	v_rcp_f32_e32 v52, v52
	v_rcp_f32_e32 v53, v53
	s_nop 0
	v_pk_mul_f32 v[52:53], v[54:55], v[52:53]
	s_nop 0
	v_pk_mul_f32 v[50:51], v[50:51], v[52:53]
	s_nop 0
	v_cvt_pk_bf16_f32 v49, v50, v51
	v_pk_mul_f32 v[50:51], v[44:45], s[100:101]
	v_exp_f32_e32 v50, v50
	v_exp_f32_e32 v51, v51
	global_store_dwordx2 v[60:61], v[48:49], off offset:32
	v_add_u32_e32 v48, 0x90, v143
	v_pk_add_f32 v[50:51], v[50:51], 1.0 op_sel_hi:[1,0]
	v_rcp_f32_e32 v50, v50
	v_rcp_f32_e32 v51, v51
	v_mad_i64_i32 v[48:49], s[2:3], v48, s0, v[134:135]
	v_pk_mul_f32 v[44:45], v[44:45], v[50:51]
	s_nop 0
	v_pk_mul_f32 v[40:41], v[40:41], v[44:45]
	v_pk_mul_f32 v[44:45], v[46:47], s[100:101]
	v_exp_f32_e32 v44, v44
	v_exp_f32_e32 v45, v45
	v_cvt_pk_bf16_f32 v40, v40, v41
	v_pk_add_f32 v[44:45], v[44:45], 1.0 op_sel_hi:[1,0]
	v_rcp_f32_e32 v44, v44
	v_rcp_f32_e32 v45, v45
	s_nop 0
	v_pk_mul_f32 v[44:45], v[46:47], v[44:45]
	s_nop 0
	v_pk_mul_f32 v[42:43], v[42:43], v[44:45]
	v_lshl_add_u64 v[44:45], v[48:49], 0, s[6:7]
	v_cvt_pk_bf16_f32 v41, v42, v43
	global_store_dwordx2 v[44:45], v[40:41], off
	v_pk_mul_f32 v[40:41], v[36:37], s[100:101]
	v_exp_f32_e32 v40, v40
	v_exp_f32_e32 v41, v41
	s_nop 0
	v_pk_add_f32 v[40:41], v[40:41], 1.0 op_sel_hi:[1,0]
	v_rcp_f32_e32 v40, v40
	v_rcp_f32_e32 v41, v41
	s_nop 0
	v_pk_mul_f32 v[36:37], v[36:37], v[40:41]
	s_nop 0
	v_pk_mul_f32 v[32:33], v[32:33], v[36:37]
	v_pk_mul_f32 v[36:37], v[38:39], s[100:101]
	v_exp_f32_e32 v36, v36
	v_exp_f32_e32 v37, v37
	v_cvt_pk_bf16_f32 v32, v32, v33
	v_pk_add_f32 v[36:37], v[36:37], 1.0 op_sel_hi:[1,0]
	v_rcp_f32_e32 v36, v36
	v_rcp_f32_e32 v37, v37
	s_nop 0
	v_pk_mul_f32 v[36:37], v[38:39], v[36:37]
	s_nop 0
	v_pk_mul_f32 v[34:35], v[34:35], v[36:37]
	s_nop 0
	v_cvt_pk_bf16_f32 v33, v34, v35
	v_pk_mul_f32 v[34:35], v[28:29], s[100:101]
	v_exp_f32_e32 v34, v34
	v_exp_f32_e32 v35, v35
	global_store_dwordx2 v[44:45], v[32:33], off offset:32
	v_add_u32_e32 v32, 0xa0, v143
	v_pk_add_f32 v[34:35], v[34:35], 1.0 op_sel_hi:[1,0]
	v_rcp_f32_e32 v34, v34
	v_rcp_f32_e32 v35, v35
	v_mad_i64_i32 v[32:33], s[2:3], v32, s0, v[134:135]
	v_pk_mul_f32 v[28:29], v[28:29], v[34:35]
	s_nop 0
	v_pk_mul_f32 v[24:25], v[24:25], v[28:29]
	v_pk_mul_f32 v[28:29], v[30:31], s[100:101]
	v_exp_f32_e32 v28, v28
	v_exp_f32_e32 v29, v29
	v_cvt_pk_bf16_f32 v24, v24, v25
	v_pk_add_f32 v[28:29], v[28:29], 1.0 op_sel_hi:[1,0]
	v_rcp_f32_e32 v28, v28
	v_rcp_f32_e32 v29, v29
	s_nop 0
	v_pk_mul_f32 v[28:29], v[30:31], v[28:29]
	s_nop 0
	v_pk_mul_f32 v[26:27], v[26:27], v[28:29]
	v_lshl_add_u64 v[28:29], v[32:33], 0, s[6:7]
	v_cvt_pk_bf16_f32 v25, v26, v27
	global_store_dwordx2 v[28:29], v[24:25], off
	v_pk_mul_f32 v[24:25], v[20:21], s[100:101]
	v_exp_f32_e32 v24, v24
	v_exp_f32_e32 v25, v25
	s_nop 0
	v_pk_add_f32 v[24:25], v[24:25], 1.0 op_sel_hi:[1,0]
	v_rcp_f32_e32 v24, v24
	v_rcp_f32_e32 v25, v25
	s_nop 0
	v_pk_mul_f32 v[20:21], v[20:21], v[24:25]
	s_nop 0
	v_pk_mul_f32 v[16:17], v[16:17], v[20:21]
	v_pk_mul_f32 v[20:21], v[22:23], s[100:101]
	v_exp_f32_e32 v20, v20
	v_exp_f32_e32 v21, v21
	v_cvt_pk_bf16_f32 v16, v16, v17
	v_pk_add_f32 v[20:21], v[20:21], 1.0 op_sel_hi:[1,0]
	v_rcp_f32_e32 v20, v20
	v_rcp_f32_e32 v21, v21
	s_nop 0
	v_pk_mul_f32 v[20:21], v[22:23], v[20:21]
	s_nop 0
	v_pk_mul_f32 v[18:19], v[18:19], v[20:21]
	s_nop 0
	v_cvt_pk_bf16_f32 v17, v18, v19
	v_pk_mul_f32 v[18:19], v[12:13], s[100:101]
	v_exp_f32_e32 v18, v18
	v_exp_f32_e32 v19, v19
	global_store_dwordx2 v[28:29], v[16:17], off offset:32
	v_add_u32_e32 v16, 0xb0, v143
	v_pk_add_f32 v[18:19], v[18:19], 1.0 op_sel_hi:[1,0]
	v_rcp_f32_e32 v18, v18
	v_rcp_f32_e32 v19, v19
	v_mad_i64_i32 v[16:17], s[2:3], v16, s0, v[134:135]
	s_mov_b64 s[2:3], -1
	v_pk_mul_f32 v[12:13], v[12:13], v[18:19]
	s_nop 0
	v_pk_mul_f32 v[8:9], v[8:9], v[12:13]
	v_pk_mul_f32 v[12:13], v[14:15], s[100:101]
	v_exp_f32_e32 v12, v12
	v_exp_f32_e32 v13, v13
	v_cvt_pk_bf16_f32 v8, v8, v9
	v_pk_add_f32 v[12:13], v[12:13], 1.0 op_sel_hi:[1,0]
	v_rcp_f32_e32 v12, v12
	v_rcp_f32_e32 v13, v13
	s_nop 0
	v_pk_mul_f32 v[12:13], v[14:15], v[12:13]
	s_nop 0
	v_pk_mul_f32 v[10:11], v[10:11], v[12:13]
	v_lshl_add_u64 v[12:13], v[16:17], 0, s[6:7]
	v_cvt_pk_bf16_f32 v9, v10, v11
	global_store_dwordx2 v[12:13], v[8:9], off
	v_pk_mul_f32 v[8:9], v[4:5], s[100:101]
	v_exp_f32_e32 v8, v8
	v_exp_f32_e32 v9, v9
	s_nop 0
	v_pk_add_f32 v[8:9], v[8:9], 1.0 op_sel_hi:[1,0]
	v_rcp_f32_e32 v8, v8
	v_rcp_f32_e32 v9, v9
	s_nop 0
	v_pk_mul_f32 v[4:5], v[4:5], v[8:9]
	s_nop 0
	v_pk_mul_f32 v[0:1], v[0:1], v[4:5]
	v_pk_mul_f32 v[4:5], v[6:7], s[100:101]
	v_exp_f32_e32 v4, v4
	v_exp_f32_e32 v5, v5
	v_cvt_pk_bf16_f32 v0, v0, v1
	v_pk_add_f32 v[4:5], v[4:5], 1.0 op_sel_hi:[1,0]
	v_rcp_f32_e32 v4, v4
	v_rcp_f32_e32 v5, v5
	s_nop 0
	v_pk_mul_f32 v[4:5], v[6:7], v[4:5]
	s_nop 0
	v_pk_mul_f32 v[2:3], v[2:3], v[4:5]
	s_nop 0
	v_cvt_pk_bf16_f32 v1, v2, v3
	global_store_dwordx2 v[12:13], v[0:1], off offset:32
	s_cbranch_vccnz .LBB0_1531
	s_andn2_b64 vcc, exec, s[12:13]
	s_cbranch_vccnz .LBB0_1530
	s_barrier
	s_branch .LBB0_1530
